# lru_tile gate GEMM: weight / bias / LDS fragment loads issued up front
# speedup vs baseline: 1.0083x; 1.0008x over previous
.LBB0_650:
	s_or_b64 exec, exec, s[10:11]
	s_lshl_b32 s4, s4, 16
	v_readlane_b32 s10, v249, 32
	s_add_u32 s10, s10, s4
	v_readlane_b32 s4, v249, 33
	s_addc_u32 s11, s4, 0
	s_ashr_i32 s4, s5, 2
	s_and_b32 s5, s4, -16
	v_and_b32_e32 v18, 15, v39
	v_bfi_b32 v36, -16, s4, v39
	s_addk_i32 s5, 0x80
	s_waitcnt vmcnt(2)
	v_cvt_pk_bf16_f32 v6, v6, v7
	v_cvt_pk_bf16_f32 v7, v8, v9
	v_cvt_pk_bf16_f32 v9, v4, v5
	v_ashrrev_i32_e32 v37, 31, v36
	v_or_b32_e32 v4, s5, v18
	v_cvt_pk_bf16_f32 v8, v2, v3
	s_movk_i32 s18, 0x110
	v_bfe_u32 v44, v39, 4, 2
	v_lshlrev_b64 v[2:3], 8, v[36:37]
	v_ashrrev_i32_e32 v5, 31, v4
	v_mul_lo_u32 v41, v22, s18
	v_lshl_add_u64 v[2:3], s[10:11], 0, v[2:3]
	v_lshlrev_b32_e32 v0, 4, v44
	v_lshlrev_b64 v[4:5], 8, v[4:5]
	s_waitcnt vmcnt(0)
	v_cvt_pk_bf16_f32 v14, v14, v15
	v_cvt_pk_bf16_f32 v15, v16, v17
	v_cvt_pk_bf16_f32 v16, v10, v11
	v_cvt_pk_bf16_f32 v17, v12, v13
	v_add3_u32 v35, 0, v41, v34
	v_lshl_add_u64 v[2:3], v[2:3], 0, v[0:1]
	v_lshl_add_u64 v[4:5], s[10:11], 0, v[4:5]
	ds_write_b128 v35, v[14:17]
	ds_write_b128 v35, v[6:9] offset:16
	s_waitcnt lgkmcnt(0)
	s_barrier
	v_lshl_add_u64 v[4:5], v[4:5], 0, v[0:1]
	global_load_dwordx4 v[70:73], v[2:3], off
	global_load_dwordx4 v[74:77], v[4:5], off
	global_load_dwordx4 v[78:81], v[2:3], off offset:64
	global_load_dwordx4 v[82:85], v[4:5], off offset:64
	global_load_dwordx4 v[86:89], v[2:3], off offset:128
	global_load_dwordx4 v[90:93], v[4:5], off offset:128
	global_load_dwordx4 v[94:97], v[2:3], off offset:192
	global_load_dwordx4 v[98:101], v[4:5], off offset:192
	v_mul_u32_u24_e32 v14, 0x110, v18
	v_add3_u32 v45, 0, v0, v14
	v_readlane_b32 s12, v250, 57
	v_readlane_b32 s13, v250, 58
	s_add_i32 s10, s68, s16
	v_add_u32_e32 v42, s10, v36
	v_ashrrev_i32_e32 v43, 31, v42
	v_lshlrev_b64 v[46:47], 2, v[42:43]
	s_movk_i32 s4, 0x50
	s_movk_i32 s10, 0x60
	s_load_dwordx2 s[4:5], s[12:13], s4 offset:0x0
	s_load_dwordx2 s[10:11], s[12:13], s10 offset:0x0
	s_waitcnt lgkmcnt(0)
	v_lshl_add_u64 v[42:43], s[4:5], 0, v[46:47]
	global_load_dword v37, v[42:43], off
	v_lshl_add_u64 v[42:43], s[10:11], 0, v[46:47]
	s_movk_i32 s4, 0x68
	global_load_dword v42, v[42:43], off
	s_load_dwordx2 s[4:5], s[12:13], s4 offset:0x0
	s_waitcnt lgkmcnt(0)
	v_lshl_add_u64 v[46:47], s[4:5], 0, v[46:47]
	global_load_dword v0, v[46:47], off
	ds_read_b128 v[102:105], v45
	ds_read_b128 v[106:109], v45 offset:4352
	ds_read_b128 v[110:113], v45 offset:8704
	ds_read_b128 v[114:117], v45 offset:13056
	ds_read_b128 v[118:121], v45 offset:64
	ds_read_b128 v[122:125], v45 offset:4416
	ds_read_b128 v[126:129], v45 offset:8768
	ds_read_b128 v[130:133], v45 offset:13120
	ds_read_b128 v[134:137], v45 offset:128
	ds_read_b128 v[50:53], v45 offset:4480
	ds_read_b128 v[54:57], v45 offset:8832
	ds_read_b128 v[58:61], v45 offset:13184
	ds_read_b128 v[62:65], v45 offset:192
	ds_read_b128 v[66:69], v45 offset:4544
	ds_read_b128 v[46:49], v45 offset:8896
	s_waitcnt vmcnt(9)
	s_waitcnt lgkmcnt(14)
	v_mfma_f32_16x16x32_bf16 v[30:33], v[102:105], v[70:73], 0
	v_mfma_f32_16x16x32_bf16 v[26:29], v[102:105], v[74:77], 0
	s_waitcnt lgkmcnt(13)
	v_mfma_f32_16x16x32_bf16 v[22:25], v[106:109], v[70:73], 0
	v_mfma_f32_16x16x32_bf16 v[18:21], v[106:109], v[74:77], 0
	s_waitcnt lgkmcnt(12)
	v_mfma_f32_16x16x32_bf16 v[14:17], v[110:113], v[70:73], 0
	v_mfma_f32_16x16x32_bf16 v[10:13], v[110:113], v[74:77], 0
	s_waitcnt lgkmcnt(11)
	v_mfma_f32_16x16x32_bf16 v[6:9], v[114:117], v[70:73], 0
	v_mfma_f32_16x16x32_bf16 v[2:5], v[114:117], v[74:77], 0
	ds_read_b128 v[102:105], v45 offset:13248
	s_waitcnt vmcnt(7)
	s_waitcnt lgkmcnt(11)
	v_mfma_f32_16x16x32_bf16 v[30:33], v[118:121], v[78:81], v[30:33]
	v_mfma_f32_16x16x32_bf16 v[26:29], v[118:121], v[82:85], v[26:29]
	s_waitcnt lgkmcnt(10)
	v_mfma_f32_16x16x32_bf16 v[22:25], v[122:125], v[78:81], v[22:25]
	v_mfma_f32_16x16x32_bf16 v[18:21], v[122:125], v[82:85], v[18:21]
	s_waitcnt lgkmcnt(9)
	v_mfma_f32_16x16x32_bf16 v[14:17], v[126:129], v[78:81], v[14:17]
	v_mfma_f32_16x16x32_bf16 v[10:13], v[126:129], v[82:85], v[10:13]
	s_waitcnt lgkmcnt(8)
	v_mfma_f32_16x16x32_bf16 v[6:9], v[130:133], v[78:81], v[6:9]
	v_mfma_f32_16x16x32_bf16 v[2:5], v[130:133], v[82:85], v[2:5]
	s_waitcnt vmcnt(5)
	s_waitcnt lgkmcnt(7)
	v_mfma_f32_16x16x32_bf16 v[30:33], v[134:137], v[86:89], v[30:33]
	v_mfma_f32_16x16x32_bf16 v[26:29], v[134:137], v[90:93], v[26:29]
	s_waitcnt lgkmcnt(6)
	v_mfma_f32_16x16x32_bf16 v[22:25], v[50:53], v[86:89], v[22:25]
	v_mfma_f32_16x16x32_bf16 v[18:21], v[50:53], v[90:93], v[18:21]
	s_waitcnt lgkmcnt(5)
	v_mfma_f32_16x16x32_bf16 v[14:17], v[54:57], v[86:89], v[14:17]
	v_mfma_f32_16x16x32_bf16 v[10:13], v[54:57], v[90:93], v[10:13]
	s_waitcnt lgkmcnt(4)
	v_mfma_f32_16x16x32_bf16 v[6:9], v[58:61], v[86:89], v[6:9]
	v_mfma_f32_16x16x32_bf16 v[2:5], v[58:61], v[90:93], v[2:5]
	s_waitcnt vmcnt(3)
	s_waitcnt lgkmcnt(3)
	v_mfma_f32_16x16x32_bf16 v[30:33], v[62:65], v[94:97], v[30:33]
	v_mfma_f32_16x16x32_bf16 v[26:29], v[62:65], v[98:101], v[26:29]
	s_waitcnt lgkmcnt(2)
	v_mfma_f32_16x16x32_bf16 v[22:25], v[66:69], v[94:97], v[22:25]
	v_mfma_f32_16x16x32_bf16 v[18:21], v[66:69], v[98:101], v[18:21]
	s_waitcnt lgkmcnt(1)
	v_mfma_f32_16x16x32_bf16 v[14:17], v[46:49], v[94:97], v[14:17]
	v_mfma_f32_16x16x32_bf16 v[10:13], v[46:49], v[98:101], v[10:13]
	s_waitcnt lgkmcnt(0)
	v_mfma_f32_16x16x32_bf16 v[6:9], v[102:105], v[94:97], v[6:9]
	v_mfma_f32_16x16x32_bf16 v[2:5], v[102:105], v[98:101], v[2:5]
	s_mov_b32 s4, 0x3f2aaaab
	s_mov_b32 s5, 0xf800000
	s_waitcnt vmcnt(2)
	v_add_f32_e32 v30, v30, v37
	v_mul_f32_e32 v30, 0xbfb8aa3b, v30
	v_exp_f32_e32 v30, v30
	v_add_f32_e32 v22, v22, v37
	v_mul_f32_e32 v22, 0xbfb8aa3b, v22
	v_exp_f32_e32 v22, v22
	v_add_f32_e32 v30, 1.0, v30
	v_rcp_f32_e32 v30, v30
	v_add_f32_e32 v23, v23, v37
	s_waitcnt vmcnt(1)
	v_add_f32_e32 v26, v26, v42
	v_mul_f32_e32 v26, 0xbfb8aa3b, v26
	v_mul_f32_e32 v30, 0xc1000000, v30
	v_exp_f32_e32 v26, v26
	v_add_f32_e32 v27, v27, v42
	v_mul_f32_e32 v27, 0xbfb8aa3b, v27
	v_exp_f32_e32 v27, v27
	v_add_f32_e32 v26, 1.0, v26
	s_waitcnt vmcnt(0)
	v_mul_f32_e32 v0, 0xbfb8aa3b, v0
	v_exp_f32_e32 v0, v0
	v_rcp_f32_e32 v26, v26
	v_add_f32_e32 v27, 1.0, v27
	v_rcp_f32_e32 v27, v27
	v_add_f32_e32 v43, 1.0, v0
	v_add_f32_e32 v45, -1.0, v43
	v_sub_f32_e32 v46, v45, v43
	v_add_f32_e32 v46, 1.0, v46
	v_sub_f32_e32 v45, v0, v45
	v_add_f32_e32 v45, v45, v46
	v_frexp_mant_f32_e32 v46, v43
	v_cmp_gt_f32_e32 vcc, s4, v46
	v_cvt_f64_f32_e32 v[46:47], v43
	v_frexp_exp_i32_f64_e32 v46, v[46:47]
	v_subbrev_co_u32_e32 v46, vcc, 0, v46, vcc
	v_sub_u32_e32 v47, 0, v46
	v_ldexp_f32 v43, v43, v47
	v_ldexp_f32 v45, v45, v47
	v_add_f32_e32 v47, -1.0, v43
	v_add_f32_e32 v48, 1.0, v47
	v_sub_f32_e32 v48, v43, v48
	v_add_f32_e32 v48, v45, v48
	v_add_f32_e32 v49, v47, v48
	v_sub_f32_e32 v47, v49, v47
	v_sub_f32_e32 v47, v48, v47
	v_add_f32_e32 v48, 1.0, v43
	v_add_f32_e32 v50, -1.0, v48
	v_sub_f32_e32 v43, v43, v50
	v_add_f32_e32 v43, v45, v43
	v_add_f32_e32 v45, v48, v43
	v_sub_f32_e32 v48, v45, v48
	v_sub_f32_e32 v43, v43, v48
	v_rcp_f32_e32 v48, v45
	v_cvt_f32_i32_e32 v46, v46
	s_mov_b32 s4, 0x3f317218
	v_add_f32_e32 v28, v28, v42
	v_mul_f32_e32 v50, v49, v48
	v_mul_f32_e32 v51, v45, v50
	v_fma_f32 v52, v50, v45, -v51
	v_fmac_f32_e32 v52, v50, v43
	v_add_f32_e32 v53, v51, v52
	v_sub_f32_e32 v54, v49, v53
	v_sub_f32_e32 v49, v49, v54
	v_sub_f32_e32 v51, v53, v51
	v_sub_f32_e32 v49, v49, v53
	v_add_f32_e32 v47, v47, v49
	v_sub_f32_e32 v49, v51, v52
	v_add_f32_e32 v47, v49, v47
	v_add_f32_e32 v49, v54, v47
	v_mul_f32_e32 v51, v48, v49
	v_mul_f32_e32 v52, v45, v51
	v_fma_f32 v45, v51, v45, -v52
	v_fmac_f32_e32 v45, v51, v43
	v_sub_f32_e32 v43, v54, v49
	v_add_f32_e32 v43, v47, v43
	v_add_f32_e32 v47, v52, v45
	v_sub_f32_e32 v53, v49, v47
	v_sub_f32_e32 v49, v49, v53
	v_sub_f32_e32 v52, v47, v52
	v_sub_f32_e32 v47, v49, v47
	v_add_f32_e32 v43, v43, v47
	v_sub_f32_e32 v45, v52, v45
	v_add_f32_e32 v43, v45, v43
	v_add_f32_e32 v45, v50, v51
	v_add_f32_e32 v43, v53, v43
	v_sub_f32_e32 v47, v45, v50
	v_mul_f32_e32 v43, v48, v43
	v_sub_f32_e32 v47, v51, v47
	v_add_f32_e32 v43, v47, v43
	v_mul_f32_e32 v50, 0x3f317218, v46
	v_add_f32_e32 v47, v45, v43
	v_fma_f32 v51, v46, s4, -v50
	v_mul_f32_e32 v48, v47, v47
	v_fmac_f32_e32 v51, 0xb102e308, v46
	v_sub_f32_e32 v45, v47, v45
	v_fmamk_f32 v49, v48, 0x3e9b6dac, v195
	v_sub_f32_e32 v43, v43, v45
	v_add_f32_e32 v45, v50, v51
	v_fmaak_f32 v49, v48, v49, 0x3f2aaada
	v_sub_f32_e32 v46, v45, v50
	v_ldexp_f32 v50, v47, 1
	v_mul_f32_e32 v47, v47, v48
	v_mul_f32_e32 v47, v47, v49
	v_add_f32_e32 v48, v50, v47
	v_sub_f32_e32 v49, v48, v50
	v_ldexp_f32 v43, v43, 1
	v_sub_f32_e32 v47, v47, v49
	v_add_f32_e32 v43, v43, v47
	v_add_f32_e32 v47, v48, v43
	v_sub_f32_e32 v48, v47, v48
	v_sub_f32_e32 v43, v43, v48
	v_add_f32_e32 v48, v45, v47
	v_sub_f32_e32 v49, v48, v45
	v_sub_f32_e32 v50, v48, v49
	v_sub_f32_e32 v46, v51, v46
	v_sub_f32_e32 v45, v45, v50
	v_sub_f32_e32 v47, v47, v49
	v_add_f32_e32 v45, v47, v45
	v_add_f32_e32 v47, v46, v43
	v_sub_f32_e32 v49, v47, v46
	v_sub_f32_e32 v50, v47, v49
	v_sub_f32_e32 v46, v46, v50
	v_sub_f32_e32 v43, v43, v49
	v_add_f32_e32 v45, v47, v45
	v_add_f32_e32 v43, v43, v46
	v_add_f32_e32 v46, v48, v45
	v_sub_f32_e32 v47, v46, v48
	v_sub_f32_e32 v45, v45, v47
	v_add_f32_e32 v43, v43, v45
	s_mov_b32 s4, 0x7f800000
	v_add_f32_e32 v43, v46, v43
	v_cmp_neq_f32_e32 vcc, s4, v0
	s_mov_b32 s4, 0x33800000
	v_mul_f32_e32 v28, 0xbfb8aa3b, v28
	v_cndmask_b32_e32 v43, v198, v43, vcc
	v_cmp_ngt_f32_e32 vcc, -1.0, v0
	v_exp_f32_e32 v28, v28
	v_add_f32_e32 v18, v18, v42
	v_cndmask_b32_e32 v43, v199, v43, vcc
	v_cmp_neq_f32_e32 vcc, -1.0, v0
	v_add_f32_e32 v28, 1.0, v28
	v_rcp_f32_e32 v28, v28
	v_cndmask_b32_e32 v43, v200, v43, vcc
	v_cmp_lt_f32_e64 vcc, |v0|, s4
	s_movk_i32 s4, 0x440
	v_mul_f32_e32 v18, 0xbfb8aa3b, v18
	v_cndmask_b32_e32 v43, v43, v0, vcc
	v_mul_f32_e32 v30, v30, v43
	v_mul_f32_e32 v30, 0x3fb8aa3b, v30
	v_exp_f32_e32 v30, v30
	v_lshl_add_u32 v0, v36, 1, 0
	v_add_f32_e32 v22, 1.0, v22
	v_exp_f32_e32 v18, v18
	v_fma_f32 v45, -v30, v30, 1.0
	v_max_f32_e32 v45, 0, v45
	v_cmp_gt_f32_e32 vcc, s5, v45
	v_mul_f32_e32 v46, 0x4f800000, v45
	v_rcp_f32_e32 v22, v22
	v_cndmask_b32_e32 v45, v45, v46, vcc
	v_sqrt_f32_e32 v46, v45
	v_add_f32_e32 v18, 1.0, v18
	v_mul_f32_e32 v23, 0xbfb8aa3b, v23
	v_exp_f32_e32 v23, v23
	v_add_u32_e32 v47, -1, v46
	v_fma_f32 v48, -v47, v46, v45
	v_cmp_ge_f32_e64 s[10:11], 0, v48
	v_add_u32_e32 v48, 1, v46
	v_add_f32_e32 v23, 1.0, v23
	v_cndmask_b32_e64 v47, v46, v47, s[10:11]
	v_fma_f32 v46, -v48, v46, v45
	v_cmp_lt_f32_e64 s[10:11], 0, v46
	v_rcp_f32_e32 v23, v23
	v_add_f32_e32 v19, v19, v42
	v_cndmask_b32_e64 v46, v47, v48, s[10:11]
	v_mul_f32_e32 v47, 0x37800000, v46
	v_cndmask_b32_e32 v46, v46, v47, vcc
	v_cmp_class_f32_e32 vcc, v45, v196
	v_mul_f32_e32 v23, 0xc1000000, v23
	v_mul_f32_e32 v23, v23, v43
	v_cndmask_b32_e32 v45, v46, v45, vcc
	v_mad_u32_u24 v46, v44, s4, v0
	ds_read_u16 v46, v46
	s_movk_i32 s4, 0x204
	v_mad_u32_u24 v47, v44, s4, v36
	v_mul_f32_e32 v26, v26, v45
	v_lshl_add_u32 v47, v47, 2, 0
	s_waitcnt lgkmcnt(0)
	v_lshlrev_b32_e32 v46, 16, v46
	v_mul_f32_e32 v26, v26, v46
	ds_write2st64_b32 v47, v30, v26 offset0:68 offset1:197
	v_add_f32_e32 v26, v31, v37
	v_mul_f32_e32 v26, 0xbfb8aa3b, v26
	v_exp_f32_e32 v26, v26
	v_lshl_or_b32 v30, v44, 2, 1
	s_movk_i32 s4, 0x81
	v_mul_f32_e32 v23, 0x3fb8aa3b, v23
	v_add_f32_e32 v26, 1.0, v26
	v_rcp_f32_e32 v26, v26
	v_exp_f32_e32 v23, v23
	v_mul_f32_e32 v19, 0xbfb8aa3b, v19
	v_exp_f32_e32 v19, v19
	v_mul_f32_e32 v26, 0xc1000000, v26
	v_mul_f32_e32 v26, v26, v43
	v_mul_f32_e32 v26, 0x3fb8aa3b, v26
	v_exp_f32_e32 v31, v26
	v_add_f32_e32 v19, 1.0, v19
	v_rcp_f32_e32 v19, v19
	v_add_f32_e32 v20, v20, v42
	v_fma_f32 v26, -v31, v31, 1.0
	v_max_f32_e32 v26, 0, v26
	v_cmp_gt_f32_e32 vcc, s5, v26
	v_mul_f32_e32 v44, 0x4f800000, v26
	v_mul_f32_e32 v20, 0xbfb8aa3b, v20
	v_cndmask_b32_e32 v26, v26, v44, vcc
	v_sqrt_f32_e32 v44, v26
	v_exp_f32_e32 v20, v20
	v_add_f32_e32 v21, v21, v42
	v_mul_f32_e32 v21, 0xbfb8aa3b, v21
	v_add_u32_e32 v45, -1, v44
	v_fma_f32 v46, -v45, v44, v26
	v_cmp_ge_f32_e64 s[10:11], 0, v46
	v_add_u32_e32 v46, 1, v44
	v_add_f32_e32 v20, 1.0, v20
	v_cndmask_b32_e64 v45, v44, v45, s[10:11]
	v_fma_f32 v44, -v46, v44, v26
	v_cmp_lt_f32_e64 s[10:11], 0, v44
	v_rcp_f32_e32 v20, v20
	v_exp_f32_e32 v21, v21
	v_cndmask_b32_e64 v44, v45, v46, s[10:11]
	v_mul_f32_e32 v45, 0x37800000, v44
	v_cndmask_b32_e32 v44, v44, v45, vcc
	v_cmp_class_f32_e32 vcc, v26, v196
	v_add_f32_e32 v14, v14, v37
	v_mul_f32_e32 v14, 0xbfb8aa3b, v14
	v_cndmask_b32_e32 v44, v44, v26, vcc
	v_mad_u32_u24 v26, v30, s18, v0
	ds_read_u16 v0, v26
	v_mul_f32_e32 v27, v27, v44
	v_exp_f32_e32 v14, v14
	v_add_f32_e32 v21, 1.0, v21
	v_add_f32_e32 v10, v10, v42
	s_waitcnt lgkmcnt(0)
	v_lshlrev_b32_e32 v45, 16, v0
	v_mad_u32_u24 v0, v30, s4, v36
	v_add_f32_e32 v30, v32, v37
	v_mul_f32_e32 v30, 0xbfb8aa3b, v30
	v_exp_f32_e32 v30, v30
	v_mul_f32_e32 v27, v27, v45
	v_lshl_add_u32 v0, v0, 2, 0
	v_rcp_f32_e32 v21, v21
	v_add_f32_e32 v30, 1.0, v30
	v_rcp_f32_e32 v30, v30
	v_mul_f32_e32 v10, 0xbfb8aa3b, v10
	v_add_f32_e32 v14, 1.0, v14
	v_exp_f32_e32 v10, v10
	v_mul_f32_e32 v30, 0xc1000000, v30
	v_mul_f32_e32 v30, v30, v43
	v_mul_f32_e32 v30, 0x3fb8aa3b, v30
	v_exp_f32_e32 v30, v30
	v_rcp_f32_e32 v14, v14
	v_add_f32_e32 v10, 1.0, v10
	v_add_f32_e32 v15, v15, v37
	v_fma_f32 v32, -v30, v30, 1.0
	v_max_f32_e32 v32, 0, v32
	v_cmp_gt_f32_e32 vcc, s5, v32
	v_mul_f32_e32 v36, 0x4f800000, v32
	v_mul_f32_e32 v15, 0xbfb8aa3b, v15
	v_cndmask_b32_e32 v32, v32, v36, vcc
	v_sqrt_f32_e32 v36, v32
	v_exp_f32_e32 v15, v15
	v_add_f32_e32 v11, v11, v42
	v_mul_f32_e32 v11, 0xbfb8aa3b, v11
	v_add_u32_e32 v44, -1, v36
	v_fma_f32 v45, -v44, v36, v32
	v_cmp_ge_f32_e64 s[10:11], 0, v45
	v_add_u32_e32 v45, 1, v36
	v_add_f32_e32 v15, 1.0, v15
	v_cndmask_b32_e64 v44, v36, v44, s[10:11]
	v_fma_f32 v36, -v45, v36, v32
	v_cmp_lt_f32_e64 s[10:11], 0, v36
	v_rcp_f32_e32 v15, v15
	v_exp_f32_e32 v11, v11
	v_cndmask_b32_e64 v36, v44, v45, s[10:11]
	v_mul_f32_e32 v44, 0x37800000, v36
	v_cndmask_b32_e32 v36, v36, v44, vcc
	v_cmp_class_f32_e32 vcc, v32, v196
	v_add_u32_e32 v44, 0x4400, v0
	ds_write2_b32 v44, v31, v30 offset1:129
	v_cndmask_b32_e32 v32, v36, v32, vcc
	ds_read_u16 v36, v26 offset:272
	v_mul_f32_e32 v28, v28, v32
	v_add_u32_e32 v30, 0xc400, v0
	v_mul_f32_e32 v15, 0xc1000000, v15
	v_mul_f32_e32 v15, v15, v43
	s_waitcnt lgkmcnt(0)
	v_lshlrev_b32_e32 v36, 16, v36
	v_mul_f32_e32 v28, v28, v36
	ds_write2_b32 v30, v27, v28 offset0:64 offset1:193
	v_add_f32_e32 v27, v33, v37
	v_mul_f32_e32 v27, 0xbfb8aa3b, v27
	v_exp_f32_e32 v27, v27
	v_add_f32_e32 v28, v29, v42
	v_mul_f32_e32 v28, 0xbfb8aa3b, v28
	v_exp_f32_e32 v28, v28
	v_add_f32_e32 v27, 1.0, v27
	v_rcp_f32_e32 v27, v27
	v_mul_f32_e32 v15, 0x3fb8aa3b, v15
	v_add_f32_e32 v28, 1.0, v28
	v_rcp_f32_e32 v28, v28
	v_mul_f32_e32 v27, 0xc1000000, v27
	v_mul_f32_e32 v27, v27, v43
	v_mul_f32_e32 v27, 0x3fb8aa3b, v27
	v_exp_f32_e32 v27, v27
	v_exp_f32_e32 v15, v15
	v_add_f32_e32 v11, 1.0, v11
	v_rcp_f32_e32 v11, v11
	v_fma_f32 v29, -v27, v27, 1.0
	v_max_f32_e32 v29, 0, v29
	v_cmp_gt_f32_e32 vcc, s5, v29
	v_mul_f32_e32 v30, 0x4f800000, v29
	ds_write_b32 v0, v27 offset:18440
	v_cndmask_b32_e32 v29, v29, v30, vcc
	v_sqrt_f32_e32 v30, v29
	v_add_f32_e32 v12, v12, v42
	v_mul_f32_e32 v12, 0xbfb8aa3b, v12
	v_exp_f32_e32 v12, v12
	v_add_u32_e32 v31, -1, v30
	v_fma_f32 v32, -v31, v30, v29
	v_cmp_ge_f32_e64 s[10:11], 0, v32
	v_add_u32_e32 v32, 1, v30
	v_add_f32_e32 v12, 1.0, v12
	v_cndmask_b32_e64 v31, v30, v31, s[10:11]
	v_fma_f32 v30, -v32, v30, v29
	v_cmp_lt_f32_e64 s[10:11], 0, v30
	v_rcp_f32_e32 v12, v12
	v_add_f32_e32 v6, v6, v37
	v_cndmask_b32_e64 v30, v31, v32, s[10:11]
	v_mul_f32_e32 v31, 0x37800000, v30
	v_cndmask_b32_e32 v30, v30, v31, vcc
	v_cmp_class_f32_e32 vcc, v29, v196
	v_mul_f32_e32 v6, 0xbfb8aa3b, v6
	v_exp_f32_e32 v6, v6
	v_cndmask_b32_e32 v29, v30, v29, vcc
	ds_read_u16 v30, v26 offset:544
	v_mul_f32_e32 v27, v28, v29
	v_add_f32_e32 v6, 1.0, v6
	v_rcp_f32_e32 v6, v6
	v_add_f32_e32 v2, v2, v42
	s_waitcnt lgkmcnt(0)
	v_lshlrev_b32_e32 v30, 16, v30
	v_mul_f32_e32 v27, v27, v30
	ds_write_b32 v0, v27 offset:51464
	v_rcp_f32_e32 v27, v18
	v_mul_f32_e32 v18, 0xc1000000, v22
	v_mul_f32_e32 v18, v18, v43
	v_mul_f32_e32 v18, 0x3fb8aa3b, v18
	v_exp_f32_e32 v22, v18
	v_mul_f32_e32 v6, 0xc1000000, v6
	v_mul_f32_e32 v6, v6, v43
	v_mul_f32_e32 v6, 0x3fb8aa3b, v6
	v_fma_f32 v18, -v22, v22, 1.0
	v_max_f32_e32 v18, 0, v18
	v_cmp_gt_f32_e32 vcc, s5, v18
	v_mul_f32_e32 v28, 0x4f800000, v18
	v_exp_f32_e32 v6, v6
	v_cndmask_b32_e32 v18, v18, v28, vcc
	v_sqrt_f32_e32 v28, v18
	v_mul_f32_e32 v2, 0xbfb8aa3b, v2
	v_exp_f32_e32 v2, v2
	v_add_f32_e32 v3, v3, v42
	v_add_u32_e32 v29, -1, v28
	v_fma_f32 v30, -v29, v28, v18
	v_cmp_ge_f32_e64 s[10:11], 0, v30
	v_add_u32_e32 v30, 1, v28
	v_add_f32_e32 v2, 1.0, v2
	v_cndmask_b32_e64 v29, v28, v29, s[10:11]
	v_fma_f32 v28, -v30, v28, v18
	v_cmp_lt_f32_e64 s[10:11], 0, v28
	v_rcp_f32_e32 v2, v2
	v_mul_f32_e32 v3, 0xbfb8aa3b, v3
	v_cndmask_b32_e64 v28, v29, v30, s[10:11]
	v_mul_f32_e32 v29, 0x37800000, v28
	v_cndmask_b32_e32 v28, v28, v29, vcc
	v_cmp_class_f32_e32 vcc, v18, v196
	v_exp_f32_e32 v3, v3
	v_add_f32_e32 v4, v4, v42
	v_cndmask_b32_e32 v28, v28, v18, vcc
	ds_read_u16 v18, v26 offset:4080
	v_mul_f32_e32 v27, v27, v28
	v_fma_f32 v28, -v23, v23, 1.0
	v_max_f32_e32 v28, 0, v28
	v_cmp_gt_f32_e32 vcc, s5, v28
	s_waitcnt lgkmcnt(0)
	v_lshlrev_b32_e32 v29, 16, v18
	v_mul_f32_e32 v27, v27, v29
	v_mul_f32_e32 v29, 0x4f800000, v28
	v_cndmask_b32_e32 v28, v28, v29, vcc
	v_sqrt_f32_e32 v29, v28
	v_add_u32_e32 v18, 0x1e3c, v0
	v_add_f32_e32 v3, 1.0, v3
	v_rcp_f32_e32 v3, v3
	v_add_u32_e32 v30, -1, v29
	v_fma_f32 v31, -v30, v29, v28
	v_cmp_ge_f32_e64 s[10:11], 0, v31
	v_add_u32_e32 v31, 1, v29
	v_mul_f32_e32 v4, 0xbfb8aa3b, v4
	v_cndmask_b32_e64 v30, v29, v30, s[10:11]
	v_fma_f32 v29, -v31, v29, v28
	v_cmp_lt_f32_e64 s[10:11], 0, v29
	v_exp_f32_e32 v4, v4
	s_movk_i32 s4, 0x80
	v_cndmask_b32_e64 v29, v30, v31, s[10:11]
	v_mul_f32_e32 v30, 0x37800000, v29
	v_cndmask_b32_e32 v29, v29, v30, vcc
	v_cmp_class_f32_e32 vcc, v28, v196
	v_add_u32_e32 v30, 0x6200, v0
	ds_write2_b32 v30, v22, v23 offset0:15 offset1:144
	v_cndmask_b32_e32 v28, v29, v28, vcc
	ds_read_u16 v29, v26 offset:4352
	v_mul_f32_e32 v19, v19, v28
	v_add_u32_e32 v22, 0xe200, v0
	v_add_f32_e32 v4, 1.0, v4
	v_rcp_f32_e32 v4, v4
	s_waitcnt lgkmcnt(0)
	v_lshlrev_b32_e32 v29, 16, v29
	v_mul_f32_e32 v19, v19, v29
	ds_write2_b32 v22, v27, v19 offset0:79 offset1:208
	v_add_f32_e32 v19, v24, v37
	v_mul_f32_e32 v19, 0xbfb8aa3b, v19
	v_exp_f32_e32 v19, v19
	s_nop 0
	v_add_f32_e32 v19, 1.0, v19
	v_rcp_f32_e32 v19, v19
	s_nop 0
	v_mul_f32_e32 v19, 0xc1000000, v19
	v_mul_f32_e32 v19, v19, v43
	v_mul_f32_e32 v19, 0x3fb8aa3b, v19
	v_exp_f32_e32 v19, v19
	s_nop 0
	v_fma_f32 v22, -v19, v19, 1.0
	v_max_f32_e32 v22, 0, v22
	v_cmp_gt_f32_e32 vcc, s5, v22
	v_mul_f32_e32 v23, 0x4f800000, v22
	s_nop 0
	v_cndmask_b32_e32 v22, v22, v23, vcc
	v_sqrt_f32_e32 v23, v22
	s_nop 0
	v_add_u32_e32 v24, -1, v23
	v_fma_f32 v27, -v24, v23, v22
	v_cmp_ge_f32_e64 s[10:11], 0, v27
	v_add_u32_e32 v27, 1, v23
	s_nop 0
	v_cndmask_b32_e64 v24, v23, v24, s[10:11]
	v_fma_f32 v23, -v27, v23, v22
	v_cmp_lt_f32_e64 s[10:11], 0, v23
	s_nop 1
	v_cndmask_b32_e64 v23, v24, v27, s[10:11]
	v_mul_f32_e32 v24, 0x37800000, v23
	v_cndmask_b32_e32 v23, v23, v24, vcc
	v_cmp_class_f32_e32 vcc, v22, v196
	s_nop 1
	v_cndmask_b32_e32 v22, v23, v22, vcc
	v_mul_f32_e32 v20, v20, v22
	v_add_f32_e32 v22, v25, v37
	v_mul_f32_e32 v22, 0xbfb8aa3b, v22
	v_exp_f32_e32 v22, v22
	ds_read_u16 v23, v26 offset:4624
	v_add_f32_e32 v22, 1.0, v22
	v_rcp_f32_e32 v22, v22
	s_waitcnt lgkmcnt(0)
	v_lshlrev_b32_e32 v23, 16, v23
	v_mul_f32_e32 v20, v20, v23
	v_mul_f32_e32 v22, 0xc1000000, v22
	v_mul_f32_e32 v22, v22, v43
	v_mul_f32_e32 v22, 0x3fb8aa3b, v22
	v_exp_f32_e32 v22, v22
	s_nop 0
	v_fma_f32 v23, -v22, v22, 1.0
	v_max_f32_e32 v23, 0, v23
	v_cmp_gt_f32_e32 vcc, s5, v23
	v_mul_f32_e32 v24, 0x4f800000, v23
	s_nop 0
	v_cndmask_b32_e32 v23, v23, v24, vcc
	v_sqrt_f32_e32 v24, v23
	s_nop 0
	v_add_u32_e32 v25, -1, v24
	v_fma_f32 v27, -v25, v24, v23
	v_cmp_ge_f32_e64 s[10:11], 0, v27
	v_add_u32_e32 v27, 1, v24
	s_nop 0
	v_cndmask_b32_e64 v25, v24, v25, s[10:11]
	v_fma_f32 v24, -v27, v24, v23
	v_cmp_lt_f32_e64 s[10:11], 0, v24
	s_nop 1
	v_cndmask_b32_e64 v24, v25, v27, s[10:11]
	v_mul_f32_e32 v25, 0x37800000, v24
	v_cndmask_b32_e32 v24, v24, v25, vcc
	v_cmp_class_f32_e32 vcc, v23, v196
	v_add_u32_e32 v25, 0x6600, v0
	ds_write2_b32 v25, v19, v22 offset0:17 offset1:146
	v_cndmask_b32_e32 v23, v24, v23, vcc
	ds_read_u16 v24, v26 offset:4896
	v_mul_f32_e32 v19, v21, v23
	v_add_u32_e32 v21, 0xe600, v0
	s_waitcnt lgkmcnt(0)
	v_lshlrev_b32_e32 v24, 16, v24
	v_mul_f32_e32 v19, v19, v24
	ds_write2_b32 v21, v20, v19 offset0:81 offset1:210
	v_rcp_f32_e32 v19, v10
	v_mul_f32_e32 v10, 0xc1000000, v14
	v_mul_f32_e32 v10, v10, v43
	v_mul_f32_e32 v10, 0x3fb8aa3b, v10
	v_exp_f32_e32 v14, v10
	s_nop 0
	v_fma_f32 v10, -v14, v14, 1.0
	v_max_f32_e32 v10, 0, v10
	v_cmp_gt_f32_e32 vcc, s5, v10
	v_mul_f32_e32 v20, 0x4f800000, v10
	s_nop 0
	v_cndmask_b32_e32 v10, v10, v20, vcc
	v_sqrt_f32_e32 v20, v10
	s_nop 0
	v_add_u32_e32 v21, -1, v20
	v_fma_f32 v22, -v21, v20, v10
	v_cmp_ge_f32_e64 s[10:11], 0, v22
	v_add_u32_e32 v22, 1, v20
	s_nop 0
	v_cndmask_b32_e64 v21, v20, v21, s[10:11]
	v_fma_f32 v20, -v22, v20, v10
	v_cmp_lt_f32_e64 s[10:11], 0, v20
	s_nop 1
	v_cndmask_b32_e64 v20, v21, v22, s[10:11]
	v_mul_f32_e32 v21, 0x37800000, v20
	v_cndmask_b32_e32 v20, v20, v21, vcc
	v_cmp_class_f32_e32 vcc, v10, v196
	s_nop 1
	v_cndmask_b32_e32 v20, v20, v10, vcc
	ds_read_u16 v10, v26 offset:8432
	v_mul_f32_e32 v19, v19, v20
	v_add_u32_e32 v20, 0x1037c, v0
	s_waitcnt lgkmcnt(0)
	v_lshlrev_b32_e32 v21, 16, v10
	v_mul_f32_e32 v19, v19, v21
	ds_write_b32 v20, v19
	v_fma_f32 v19, -v15, v15, 1.0
	v_max_f32_e32 v19, 0, v19
	v_cmp_gt_f32_e32 vcc, s5, v19
	v_mul_f32_e32 v20, 0x4f800000, v19
	v_add_u32_e32 v10, 0x3e7c, v0
	v_cndmask_b32_e32 v19, v19, v20, vcc
	v_sqrt_f32_e32 v20, v19
	s_nop 0
	v_add_u32_e32 v21, -1, v20
	v_fma_f32 v22, -v21, v20, v19
	v_cmp_ge_f32_e64 s[10:11], 0, v22
	v_add_u32_e32 v22, 1, v20
	s_nop 0
	v_cndmask_b32_e64 v21, v20, v21, s[10:11]
	v_fma_f32 v20, -v22, v20, v19
	v_cmp_lt_f32_e64 s[10:11], 0, v20
	s_nop 1
	v_cndmask_b32_e64 v20, v21, v22, s[10:11]
	v_mul_f32_e32 v21, 0x37800000, v20
	v_cndmask_b32_e32 v20, v20, v21, vcc
	v_add_u32_e32 v21, 0x8200, v0
	ds_write2_b32 v21, v14, v15 offset0:31 offset1:160
	v_add_f32_e32 v14, v16, v37
	v_mul_f32_e32 v14, 0xbfb8aa3b, v14
	v_exp_f32_e32 v14, v14
	v_cmp_class_f32_e32 vcc, v19, v196
	v_add_f32_e32 v14, 1.0, v14
	v_rcp_f32_e32 v14, v14
	v_cndmask_b32_e32 v19, v20, v19, vcc
	ds_read_u16 v20, v26 offset:8704
	v_mul_f32_e32 v11, v11, v19
	v_mul_f32_e32 v14, 0xc1000000, v14
	v_mul_f32_e32 v14, v14, v43
	v_mul_f32_e32 v14, 0x3fb8aa3b, v14
	v_exp_f32_e32 v14, v14
	s_waitcnt lgkmcnt(0)
	v_lshlrev_b32_e32 v20, 16, v20
	v_mul_f32_e32 v11, v11, v20
	v_fma_f32 v15, -v14, v14, 1.0
	v_max_f32_e32 v15, 0, v15
	v_cmp_gt_f32_e32 vcc, s5, v15
	v_mul_f32_e32 v16, 0x4f800000, v15
	s_nop 0
	v_cndmask_b32_e32 v15, v15, v16, vcc
	v_sqrt_f32_e32 v16, v15
	s_nop 0
	v_add_u32_e32 v19, -1, v16
	v_fma_f32 v20, -v19, v16, v15
	v_cmp_ge_f32_e64 s[10:11], 0, v20
	v_add_u32_e32 v20, 1, v16
	s_nop 0
	v_cndmask_b32_e64 v19, v16, v19, s[10:11]
	v_fma_f32 v16, -v20, v16, v15
	v_cmp_lt_f32_e64 s[10:11], 0, v16
	s_nop 1
	v_cndmask_b32_e64 v16, v19, v20, s[10:11]
	v_mul_f32_e32 v19, 0x37800000, v16
	v_cndmask_b32_e32 v16, v16, v19, vcc
	v_cmp_class_f32_e32 vcc, v15, v196
	s_nop 1
	v_cndmask_b32_e32 v15, v16, v15, vcc
	ds_read_u16 v16, v26 offset:8976
	v_mul_f32_e32 v12, v12, v15
	v_add_u32_e32 v15, 0xe600, v18
	s_waitcnt lgkmcnt(0)
	v_lshlrev_b32_e32 v16, 16, v16
	v_mul_f32_e32 v12, v12, v16
	ds_write2_b32 v15, v11, v12 offset0:81 offset1:210
	v_add_f32_e32 v11, v17, v37
	v_mul_f32_e32 v11, 0xbfb8aa3b, v11
	v_exp_f32_e32 v11, v11
	v_add_f32_e32 v12, v13, v42
	v_mul_f32_e32 v12, 0xbfb8aa3b, v12
	v_exp_f32_e32 v12, v12
	v_add_f32_e32 v11, 1.0, v11
	v_rcp_f32_e32 v11, v11
	v_add_f32_e32 v12, 1.0, v12
	v_rcp_f32_e32 v12, v12
	v_mul_f32_e32 v11, 0xc1000000, v11
	v_mul_f32_e32 v11, v11, v43
	v_mul_f32_e32 v11, 0x3fb8aa3b, v11
	v_exp_f32_e32 v11, v11
	s_nop 0
	v_fma_f32 v13, -v11, v11, 1.0
	v_max_f32_e32 v13, 0, v13
	v_cmp_gt_f32_e32 vcc, s5, v13
	v_mul_f32_e32 v15, 0x4f800000, v13
	s_nop 0
	v_cndmask_b32_e32 v13, v13, v15, vcc
	v_sqrt_f32_e32 v15, v13
	s_nop 0
	v_add_u32_e32 v16, -1, v15
	v_fma_f32 v17, -v16, v15, v13
	v_cmp_ge_f32_e64 s[10:11], 0, v17
	v_add_u32_e32 v17, 1, v15
	s_nop 0
	v_cndmask_b32_e64 v16, v15, v16, s[10:11]
	v_fma_f32 v15, -v17, v15, v13
	v_cmp_lt_f32_e64 s[10:11], 0, v15
	s_nop 1
	v_cndmask_b32_e64 v15, v16, v17, s[10:11]
	v_mul_f32_e32 v16, 0x37800000, v15
	v_cndmask_b32_e32 v15, v15, v16, vcc
	v_cmp_class_f32_e32 vcc, v13, v196
	v_add_u32_e32 v16, 0x8600, v0
	ds_write2_b32 v16, v14, v11 offset0:33 offset1:162
	v_cndmask_b32_e32 v13, v15, v13, vcc
	ds_read_u16 v15, v26 offset:9248
	v_mul_f32_e32 v11, v12, v13
	s_waitcnt lgkmcnt(0)
	v_lshlrev_b32_e32 v15, 16, v15
	v_mul_f32_e32 v11, v11, v15
	ds_write_b32 v18, v11 offset:60236
	v_fma_f32 v11, -v6, v6, 1.0
	v_max_f32_e32 v11, 0, v11
	v_cmp_gt_f32_e32 vcc, s5, v11
	v_mul_f32_e32 v12, 0x4f800000, v11
	s_nop 0
	v_cndmask_b32_e32 v11, v11, v12, vcc
	v_sqrt_f32_e32 v12, v11
	s_nop 0
	v_add_u32_e32 v13, -1, v12
	v_fma_f32 v14, -v13, v12, v11
	v_cmp_ge_f32_e64 s[10:11], 0, v14
	v_add_u32_e32 v14, 1, v12
	s_nop 0
	v_cndmask_b32_e64 v13, v12, v13, s[10:11]
	v_fma_f32 v12, -v14, v12, v11
	v_cmp_lt_f32_e64 s[10:11], 0, v12
	s_nop 1
	v_cndmask_b32_e64 v12, v13, v14, s[10:11]
	v_mul_f32_e32 v13, 0x37800000, v12
	v_cndmask_b32_e32 v12, v12, v13, vcc
	v_cmp_class_f32_e32 vcc, v11, v196
	s_nop 1
	v_cndmask_b32_e32 v11, v12, v11, vcc
	ds_read_u16 v12, v26 offset:12784
	v_mul_f32_e32 v2, v2, v11
	v_add_u32_e32 v11, 0x123bc, v0
	s_waitcnt lgkmcnt(0)
	v_lshlrev_b32_e32 v12, 16, v12
	v_mul_f32_e32 v2, v2, v12
	ds_write_b32 v11, v2
	v_add_f32_e32 v2, v7, v37
	v_mul_f32_e32 v2, 0xbfb8aa3b, v2
	v_exp_f32_e32 v2, v2
	s_nop 0
	v_add_f32_e32 v2, 1.0, v2
	v_rcp_f32_e32 v2, v2
	s_nop 0
	v_mul_f32_e32 v2, 0xc1000000, v2
	v_mul_f32_e32 v2, v2, v43
	v_mul_f32_e32 v2, 0x3fb8aa3b, v2
	v_exp_f32_e32 v2, v2
	s_nop 0
	v_fma_f32 v7, -v2, v2, 1.0
	v_max_f32_e32 v7, 0, v7
	v_cmp_gt_f32_e32 vcc, s5, v7
	v_mul_f32_e32 v11, 0x4f800000, v7
	s_nop 0
	v_cndmask_b32_e32 v7, v7, v11, vcc
	v_sqrt_f32_e32 v11, v7
	s_nop 0
	v_add_u32_e32 v12, -1, v11
	v_fma_f32 v13, -v12, v11, v7
	v_cmp_ge_f32_e64 s[10:11], 0, v13
	v_add_u32_e32 v13, 1, v11
	s_nop 0
	v_cndmask_b32_e64 v12, v11, v12, s[10:11]
	v_fma_f32 v11, -v13, v11, v7
	v_cmp_lt_f32_e64 s[10:11], 0, v11
	s_nop 1
	v_cndmask_b32_e64 v11, v12, v13, s[10:11]
	v_mul_f32_e32 v12, 0x37800000, v11
	v_cndmask_b32_e32 v11, v11, v12, vcc
	v_cmp_class_f32_e32 vcc, v7, v196
	v_add_u32_e32 v12, 0xa200, v0
	ds_write2_b32 v12, v6, v2 offset0:47 offset1:176
	v_cndmask_b32_e32 v7, v11, v7, vcc
	ds_read_u16 v11, v26 offset:13056
	v_mul_f32_e32 v2, v3, v7
	v_add_u32_e32 v0, 0xa600, v0
	s_waitcnt lgkmcnt(0)
	v_lshlrev_b32_e32 v11, 16, v11
	v_mul_f32_e32 v3, v2, v11
	v_add_f32_e32 v2, v8, v37
	v_mul_f32_e32 v2, 0xbfb8aa3b, v2
	v_exp_f32_e32 v2, v2
	s_nop 0
	v_add_f32_e32 v2, 1.0, v2
	v_rcp_f32_e32 v2, v2
	s_nop 0
	v_mul_f32_e32 v2, 0xc1000000, v2
	v_mul_f32_e32 v2, v2, v43
	v_mul_f32_e32 v2, 0x3fb8aa3b, v2
	v_exp_f32_e32 v2, v2
	s_nop 0
	v_fma_f32 v6, -v2, v2, 1.0
	v_max_f32_e32 v6, 0, v6
	v_cmp_gt_f32_e32 vcc, s5, v6
	v_mul_f32_e32 v7, 0x4f800000, v6
	s_nop 0
	v_cndmask_b32_e32 v6, v6, v7, vcc
	v_sqrt_f32_e32 v7, v6
	s_nop 0
	v_add_u32_e32 v8, -1, v7
	v_fma_f32 v11, -v8, v7, v6
	v_cmp_ge_f32_e64 s[10:11], 0, v11
	v_add_u32_e32 v11, 1, v7
	s_nop 0
	v_cndmask_b32_e64 v8, v7, v8, s[10:11]
	v_fma_f32 v7, -v11, v7, v6
	v_cmp_lt_f32_e64 s[10:11], 0, v7
	s_nop 1
	v_cndmask_b32_e64 v7, v8, v11, s[10:11]
	v_mul_f32_e32 v8, 0x37800000, v7
	v_cndmask_b32_e32 v7, v7, v8, vcc
	v_cmp_class_f32_e32 vcc, v6, v196
	s_nop 1
	v_cndmask_b32_e32 v6, v7, v6, vcc
	ds_read_u16 v7, v26 offset:13328
	v_mul_f32_e32 v4, v4, v6
	v_add_u32_e32 v6, 0xe600, v10
	s_waitcnt lgkmcnt(0)
	v_lshlrev_b32_e32 v7, 16, v7
	v_mul_f32_e32 v4, v4, v7
	ds_write2_b32 v6, v3, v4 offset0:81 offset1:210
	v_add_f32_e32 v3, v9, v37
	v_mul_f32_e32 v3, 0xbfb8aa3b, v3
	v_exp_f32_e32 v3, v3
	s_nop 0
	v_add_f32_e32 v3, 1.0, v3
	v_rcp_f32_e32 v4, v3
	v_add_f32_e32 v3, v5, v42
	v_mul_f32_e32 v3, 0xbfb8aa3b, v3
	v_exp_f32_e32 v3, v3
	v_mul_f32_e32 v4, 0xc1000000, v4
	v_mul_f32_e32 v4, v4, v43
	v_mul_f32_e32 v4, 0x3fb8aa3b, v4
	v_exp_f32_e32 v4, v4
	v_add_f32_e32 v3, 1.0, v3
	v_rcp_f32_e32 v3, v3
	v_fma_f32 v5, -v4, v4, 1.0
	v_max_f32_e32 v5, 0, v5
	v_cmp_gt_f32_e32 vcc, s5, v5
	v_mul_f32_e32 v6, 0x4f800000, v5
	ds_write2_b32 v0, v2, v4 offset0:49 offset1:178
	v_cndmask_b32_e32 v5, v5, v6, vcc
	v_sqrt_f32_e32 v6, v5
	s_nop 0
	v_add_u32_e32 v7, -1, v6
	v_fma_f32 v8, -v7, v6, v5
	v_cmp_ge_f32_e64 s[10:11], 0, v8
	v_add_u32_e32 v8, 1, v6
	s_nop 0
	v_cndmask_b32_e64 v7, v6, v7, s[10:11]
	v_fma_f32 v6, -v8, v6, v5
	v_cmp_lt_f32_e64 s[10:11], 0, v6
	s_nop 1
	v_cndmask_b32_e64 v6, v7, v8, s[10:11]
	v_mul_f32_e32 v7, 0x37800000, v6
	v_cndmask_b32_e32 v6, v6, v7, vcc
	v_cmp_class_f32_e32 vcc, v5, v196
	s_nop 1
	v_cndmask_b32_e32 v5, v6, v5, vcc
	ds_read_u16 v6, v26 offset:13600
	v_mul_f32_e32 v0, v3, v5
	v_cmp_gt_i32_e32 vcc, s4, v39
	s_waitcnt lgkmcnt(0)
	v_lshlrev_b32_e32 v6, 16, v6
	v_mul_f32_e32 v0, v0, v6
	ds_write_b32 v10, v0 offset:60236
	s_waitcnt lgkmcnt(0)
	s_barrier
	s_and_saveexec_b64 s[10:11], vcc
	s_cbranch_execz .LBB0_654
	v_readlane_b32 s4, v250, 40
	v_lshl_add_u32 v0, v39, 1, 0
	v_mov_b32_e32 v3, 0
	v_lshl_add_u32 v4, v39, 2, s4
	v_mov_b32_e32 v2, 1.0
	s_movk_i32 s4, 0xbc00
	v_add_u32_e32 v8, 0x14600, v0
	v_add_u32_e32 v5, 0x0, v4
	ds_read2_b32 v[70:71], v5 offset1:129
	v_add_u32_e32 v6, 0x8100, v4
	ds_read2_b32 v[102:103], v6 offset1:129
	v_add_u32_e32 v5, 0x408, v4
	ds_read2_b32 v[72:73], v5 offset1:129
	v_add_u32_e32 v6, 0x8508, v4
	ds_read2_b32 v[104:105], v6 offset1:129
	v_add_u32_e32 v5, 0x810, v4
	ds_read2_b32 v[74:75], v5 offset1:129
	v_add_u32_e32 v6, 0x8910, v4
	ds_read2_b32 v[106:107], v6 offset1:129
	v_add_u32_e32 v5, 0xc18, v4
	ds_read2_b32 v[76:77], v5 offset1:129
	v_add_u32_e32 v6, 0x8d18, v4
	ds_read2_b32 v[108:109], v6 offset1:129
	v_add_u32_e32 v5, 0x1020, v4
	ds_read2_b32 v[78:79], v5 offset1:129
	v_add_u32_e32 v6, 0x9120, v4
	ds_read2_b32 v[110:111], v6 offset1:129
	v_add_u32_e32 v5, 0x1428, v4
	ds_read2_b32 v[80:81], v5 offset1:129
	v_add_u32_e32 v6, 0x9528, v4
	ds_read2_b32 v[112:113], v6 offset1:129
	v_add_u32_e32 v5, 0x1830, v4
	ds_read2_b32 v[82:83], v5 offset1:129
	v_add_u32_e32 v6, 0x9930, v4
	ds_read2_b32 v[114:115], v6 offset1:129
	v_add_u32_e32 v5, 0x1c38, v4
	ds_read2_b32 v[84:85], v5 offset1:129
	v_add_u32_e32 v6, 0x9d38, v4
	ds_read2_b32 v[116:117], v6 offset1:129
	v_add_u32_e32 v5, 0x2040, v4
	ds_read2_b32 v[86:87], v5 offset1:129
	v_add_u32_e32 v6, 0xa140, v4
	ds_read2_b32 v[118:119], v6 offset1:129
	v_add_u32_e32 v5, 0x2448, v4
	ds_read2_b32 v[88:89], v5 offset1:129
	v_add_u32_e32 v6, 0xa548, v4
	ds_read2_b32 v[120:121], v6 offset1:129
	v_add_u32_e32 v5, 0x2850, v4
	ds_read2_b32 v[90:91], v5 offset1:129
	v_add_u32_e32 v6, 0xa950, v4
	ds_read2_b32 v[122:123], v6 offset1:129
	v_add_u32_e32 v5, 0x2c58, v4
	ds_read2_b32 v[92:93], v5 offset1:129
	v_add_u32_e32 v6, 0xad58, v4
	ds_read2_b32 v[124:125], v6 offset1:129
	v_add_u32_e32 v5, 0x3060, v4
	ds_read2_b32 v[94:95], v5 offset1:129
	v_add_u32_e32 v6, 0xb160, v4
	ds_read2_b32 v[126:127], v6 offset1:129
	v_add_u32_e32 v5, 0x3468, v4
	ds_read2_b32 v[96:97], v5 offset1:129
	v_add_u32_e32 v6, 0xb568, v4
	ds_read2_b32 v[128:129], v6 offset1:129
	v_add_u32_e32 v5, 0x3870, v4
	ds_read2_b32 v[98:99], v5 offset1:129
	v_add_u32_e32 v6, 0xb970, v4
	ds_read2_b32 v[130:131], v6 offset1:129
	v_add_u32_e32 v5, 0x3c78, v4
	ds_read2_b32 v[100:101], v5 offset1:129
	v_add_u32_e32 v6, 0xbd78, v4
	ds_read2_b32 v[132:133], v6 offset1:129
	s_waitcnt lgkmcnt(0)
	v_mul_f32_e32 v2, v2, v70
	v_fma_f32 v3, v3, v70, v102
	v_cvt_pk_bf16_f32 v9, v3, s0
	ds_write_b16 v0, v9
	v_cvt_pk_bf16_f32 v10, v2, s0
	ds_write_b16 v8, v10
	v_mul_f32_e32 v2, v2, v71
	v_fma_f32 v3, v3, v71, v103
	v_cvt_pk_bf16_f32 v11, v3, s0
	ds_write_b16 v0, v11 offset:272
	v_cvt_pk_bf16_f32 v12, v2, s0
	ds_write_b16 v8, v12 offset:272
	v_mul_f32_e32 v2, v2, v72
	v_fma_f32 v3, v3, v72, v104
	v_cvt_pk_bf16_f32 v9, v3, s0
	ds_write_b16 v0, v9 offset:544
	v_cvt_pk_bf16_f32 v10, v2, s0
	ds_write_b16 v8, v10 offset:544
	v_mul_f32_e32 v2, v2, v73
	v_fma_f32 v3, v3, v73, v105
	v_cvt_pk_bf16_f32 v11, v3, s0
	ds_write_b16 v0, v11 offset:816
	v_cvt_pk_bf16_f32 v12, v2, s0
	ds_write_b16 v8, v12 offset:816
	v_mul_f32_e32 v2, v2, v74
	v_fma_f32 v3, v3, v74, v106
	v_cvt_pk_bf16_f32 v9, v3, s0
	ds_write_b16 v0, v9 offset:1088
	v_cvt_pk_bf16_f32 v10, v2, s0
	ds_write_b16 v8, v10 offset:1088
	v_mul_f32_e32 v2, v2, v75
	v_fma_f32 v3, v3, v75, v107
	v_cvt_pk_bf16_f32 v11, v3, s0
	ds_write_b16 v0, v11 offset:1360
	v_cvt_pk_bf16_f32 v12, v2, s0
	ds_write_b16 v8, v12 offset:1360
	v_mul_f32_e32 v2, v2, v76
	v_fma_f32 v3, v3, v76, v108
	v_cvt_pk_bf16_f32 v9, v3, s0
	ds_write_b16 v0, v9 offset:1632
	v_cvt_pk_bf16_f32 v10, v2, s0
	ds_write_b16 v8, v10 offset:1632
	v_mul_f32_e32 v2, v2, v77
	v_fma_f32 v3, v3, v77, v109
	v_cvt_pk_bf16_f32 v11, v3, s0
	ds_write_b16 v0, v11 offset:1904
	v_cvt_pk_bf16_f32 v12, v2, s0
	ds_write_b16 v8, v12 offset:1904
	v_mul_f32_e32 v2, v2, v78
	v_fma_f32 v3, v3, v78, v110
	v_cvt_pk_bf16_f32 v9, v3, s0
	ds_write_b16 v0, v9 offset:2176
	v_cvt_pk_bf16_f32 v10, v2, s0
	ds_write_b16 v8, v10 offset:2176
	v_mul_f32_e32 v2, v2, v79
	v_fma_f32 v3, v3, v79, v111
	v_cvt_pk_bf16_f32 v11, v3, s0
	ds_write_b16 v0, v11 offset:2448
	v_cvt_pk_bf16_f32 v12, v2, s0
	ds_write_b16 v8, v12 offset:2448
	v_mul_f32_e32 v2, v2, v80
	v_fma_f32 v3, v3, v80, v112
	v_cvt_pk_bf16_f32 v9, v3, s0
	ds_write_b16 v0, v9 offset:2720
	v_cvt_pk_bf16_f32 v10, v2, s0
	ds_write_b16 v8, v10 offset:2720
	v_mul_f32_e32 v2, v2, v81
	v_fma_f32 v3, v3, v81, v113
	v_cvt_pk_bf16_f32 v11, v3, s0
	ds_write_b16 v0, v11 offset:2992
	v_cvt_pk_bf16_f32 v12, v2, s0
	ds_write_b16 v8, v12 offset:2992
	v_mul_f32_e32 v2, v2, v82
	v_fma_f32 v3, v3, v82, v114
	v_cvt_pk_bf16_f32 v9, v3, s0
	ds_write_b16 v0, v9 offset:3264
	v_cvt_pk_bf16_f32 v10, v2, s0
	ds_write_b16 v8, v10 offset:3264
	v_mul_f32_e32 v2, v2, v83
	v_fma_f32 v3, v3, v83, v115
	v_cvt_pk_bf16_f32 v11, v3, s0
	ds_write_b16 v0, v11 offset:3536
	v_cvt_pk_bf16_f32 v12, v2, s0
	ds_write_b16 v8, v12 offset:3536
	v_mul_f32_e32 v2, v2, v84
	v_fma_f32 v3, v3, v84, v116
	v_cvt_pk_bf16_f32 v9, v3, s0
	ds_write_b16 v0, v9 offset:3808
	v_cvt_pk_bf16_f32 v10, v2, s0
	ds_write_b16 v8, v10 offset:3808
	v_mul_f32_e32 v2, v2, v85
	v_fma_f32 v3, v3, v85, v117
	v_cvt_pk_bf16_f32 v11, v3, s0
	ds_write_b16 v0, v11 offset:4080
	v_cvt_pk_bf16_f32 v12, v2, s0
	ds_write_b16 v8, v12 offset:4080
	v_mul_f32_e32 v2, v2, v86
	v_fma_f32 v3, v3, v86, v118
	v_cvt_pk_bf16_f32 v9, v3, s0
	ds_write_b16 v0, v9 offset:4352
	v_cvt_pk_bf16_f32 v10, v2, s0
	ds_write_b16 v8, v10 offset:4352
	v_mul_f32_e32 v2, v2, v87
	v_fma_f32 v3, v3, v87, v119
	v_cvt_pk_bf16_f32 v11, v3, s0
	ds_write_b16 v0, v11 offset:4624
	v_cvt_pk_bf16_f32 v12, v2, s0
	ds_write_b16 v8, v12 offset:4624
	v_mul_f32_e32 v2, v2, v88
	v_fma_f32 v3, v3, v88, v120
	v_cvt_pk_bf16_f32 v9, v3, s0
	ds_write_b16 v0, v9 offset:4896
	v_cvt_pk_bf16_f32 v10, v2, s0
	ds_write_b16 v8, v10 offset:4896
	v_mul_f32_e32 v2, v2, v89
	v_fma_f32 v3, v3, v89, v121
	v_cvt_pk_bf16_f32 v11, v3, s0
	ds_write_b16 v0, v11 offset:5168
	v_cvt_pk_bf16_f32 v12, v2, s0
	ds_write_b16 v8, v12 offset:5168
	v_mul_f32_e32 v2, v2, v90
	v_fma_f32 v3, v3, v90, v122
	v_cvt_pk_bf16_f32 v9, v3, s0
	ds_write_b16 v0, v9 offset:5440
	v_cvt_pk_bf16_f32 v10, v2, s0
	ds_write_b16 v8, v10 offset:5440
	v_mul_f32_e32 v2, v2, v91
	v_fma_f32 v3, v3, v91, v123
	v_cvt_pk_bf16_f32 v11, v3, s0
	ds_write_b16 v0, v11 offset:5712
	v_cvt_pk_bf16_f32 v12, v2, s0
	ds_write_b16 v8, v12 offset:5712
	v_mul_f32_e32 v2, v2, v92
	v_fma_f32 v3, v3, v92, v124
	v_cvt_pk_bf16_f32 v9, v3, s0
	ds_write_b16 v0, v9 offset:5984
	v_cvt_pk_bf16_f32 v10, v2, s0
	ds_write_b16 v8, v10 offset:5984
	v_mul_f32_e32 v2, v2, v93
	v_fma_f32 v3, v3, v93, v125
	v_cvt_pk_bf16_f32 v11, v3, s0
	ds_write_b16 v0, v11 offset:6256
	v_cvt_pk_bf16_f32 v12, v2, s0
	ds_write_b16 v8, v12 offset:6256
	v_mul_f32_e32 v2, v2, v94
	v_fma_f32 v3, v3, v94, v126
	v_cvt_pk_bf16_f32 v9, v3, s0
	ds_write_b16 v0, v9 offset:6528
	v_cvt_pk_bf16_f32 v10, v2, s0
	ds_write_b16 v8, v10 offset:6528
	v_mul_f32_e32 v2, v2, v95
	v_fma_f32 v3, v3, v95, v127
	v_cvt_pk_bf16_f32 v11, v3, s0
	ds_write_b16 v0, v11 offset:6800
	v_cvt_pk_bf16_f32 v12, v2, s0
	ds_write_b16 v8, v12 offset:6800
	v_mul_f32_e32 v2, v2, v96
	v_fma_f32 v3, v3, v96, v128
	v_cvt_pk_bf16_f32 v9, v3, s0
	ds_write_b16 v0, v9 offset:7072
	v_cvt_pk_bf16_f32 v10, v2, s0
	ds_write_b16 v8, v10 offset:7072
	v_mul_f32_e32 v2, v2, v97
	v_fma_f32 v3, v3, v97, v129
	v_cvt_pk_bf16_f32 v11, v3, s0
	ds_write_b16 v0, v11 offset:7344
	v_cvt_pk_bf16_f32 v12, v2, s0
	ds_write_b16 v8, v12 offset:7344
	v_mul_f32_e32 v2, v2, v98
	v_fma_f32 v3, v3, v98, v130
	v_cvt_pk_bf16_f32 v9, v3, s0
	ds_write_b16 v0, v9 offset:7616
	v_cvt_pk_bf16_f32 v10, v2, s0
	ds_write_b16 v8, v10 offset:7616
	v_mul_f32_e32 v2, v2, v99
	v_fma_f32 v3, v3, v99, v131
	v_cvt_pk_bf16_f32 v11, v3, s0
	ds_write_b16 v0, v11 offset:7888
	v_cvt_pk_bf16_f32 v12, v2, s0
	ds_write_b16 v8, v12 offset:7888
	v_mul_f32_e32 v2, v2, v100
	v_fma_f32 v3, v3, v100, v132
	v_cvt_pk_bf16_f32 v9, v3, s0
	ds_write_b16 v0, v9 offset:8160
	v_cvt_pk_bf16_f32 v10, v2, s0
	ds_write_b16 v8, v10 offset:8160
	v_mul_f32_e32 v2, v2, v101
	v_fma_f32 v3, v3, v101, v133
	v_cvt_pk_bf16_f32 v11, v3, s0
	ds_write_b16 v0, v11 offset:8432
	v_cvt_pk_bf16_f32 v12, v2, s0
	ds_write_b16 v8, v12 offset:8432
	v_add_u32_e32 v5, 0x4080, v4
	ds_read2_b32 v[70:71], v5 offset1:129
	v_add_u32_e32 v6, 0xc180, v4
	ds_read2_b32 v[102:103], v6 offset1:129
	v_add_u32_e32 v5, 0x4488, v4
	ds_read2_b32 v[72:73], v5 offset1:129
	v_add_u32_e32 v6, 0xc588, v4
	ds_read2_b32 v[104:105], v6 offset1:129
	v_add_u32_e32 v5, 0x4890, v4
	ds_read2_b32 v[74:75], v5 offset1:129
	v_add_u32_e32 v6, 0xc990, v4
	ds_read2_b32 v[106:107], v6 offset1:129
	v_add_u32_e32 v5, 0x4c98, v4
	ds_read2_b32 v[76:77], v5 offset1:129
	v_add_u32_e32 v6, 0xcd98, v4
	ds_read2_b32 v[108:109], v6 offset1:129
	v_add_u32_e32 v5, 0x50a0, v4
	ds_read2_b32 v[78:79], v5 offset1:129
	v_add_u32_e32 v6, 0xd1a0, v4
	ds_read2_b32 v[110:111], v6 offset1:129
	v_add_u32_e32 v5, 0x54a8, v4
	ds_read2_b32 v[80:81], v5 offset1:129
	v_add_u32_e32 v6, 0xd5a8, v4
	ds_read2_b32 v[112:113], v6 offset1:129
	v_add_u32_e32 v5, 0x58b0, v4
	ds_read2_b32 v[82:83], v5 offset1:129
	v_add_u32_e32 v6, 0xd9b0, v4
	ds_read2_b32 v[114:115], v6 offset1:129
	v_add_u32_e32 v5, 0x5cb8, v4
	ds_read2_b32 v[84:85], v5 offset1:129
	v_add_u32_e32 v6, 0xddb8, v4
	ds_read2_b32 v[116:117], v6 offset1:129
	v_add_u32_e32 v5, 0x60c0, v4
	ds_read2_b32 v[86:87], v5 offset1:129
	v_add_u32_e32 v6, 0xe1c0, v4
	ds_read2_b32 v[118:119], v6 offset1:129
	v_add_u32_e32 v5, 0x64c8, v4
	ds_read2_b32 v[88:89], v5 offset1:129
	v_add_u32_e32 v6, 0xe5c8, v4
	ds_read2_b32 v[120:121], v6 offset1:129
	v_add_u32_e32 v5, 0x68d0, v4
	ds_read2_b32 v[90:91], v5 offset1:129
	v_add_u32_e32 v6, 0xe9d0, v4
	ds_read2_b32 v[122:123], v6 offset1:129
	v_add_u32_e32 v5, 0x6cd8, v4
	ds_read2_b32 v[92:93], v5 offset1:129
	v_add_u32_e32 v6, 0xedd8, v4
	ds_read2_b32 v[124:125], v6 offset1:129
	v_add_u32_e32 v5, 0x70e0, v4
	ds_read2_b32 v[94:95], v5 offset1:129
	v_add_u32_e32 v6, 0xf1e0, v4
	ds_read2_b32 v[126:127], v6 offset1:129
	v_add_u32_e32 v5, 0x74e8, v4
	ds_read2_b32 v[96:97], v5 offset1:129
	v_add_u32_e32 v6, 0xf5e8, v4
	ds_read2_b32 v[128:129], v6 offset1:129
	v_add_u32_e32 v5, 0x78f0, v4
	ds_read2_b32 v[98:99], v5 offset1:129
	v_add_u32_e32 v6, 0xf9f0, v4
	ds_read2_b32 v[130:131], v6 offset1:129
	v_add_u32_e32 v5, 0x7cf8, v4
	ds_read2_b32 v[100:101], v5 offset1:129
	v_add_u32_e32 v6, 0xfdf8, v4
	ds_read2_b32 v[132:133], v6 offset1:129
	s_waitcnt lgkmcnt(0)
	v_mul_f32_e32 v2, v2, v70
	v_fma_f32 v3, v3, v70, v102
	v_cvt_pk_bf16_f32 v9, v3, s0
	ds_write_b16 v0, v9 offset:8704
	v_cvt_pk_bf16_f32 v10, v2, s0
	ds_write_b16 v8, v10 offset:8704
	v_mul_f32_e32 v2, v2, v71
	v_fma_f32 v3, v3, v71, v103
	v_cvt_pk_bf16_f32 v11, v3, s0
	ds_write_b16 v0, v11 offset:8976
	v_cvt_pk_bf16_f32 v12, v2, s0
	ds_write_b16 v8, v12 offset:8976
	v_mul_f32_e32 v2, v2, v72
	v_fma_f32 v3, v3, v72, v104
	v_cvt_pk_bf16_f32 v9, v3, s0
	ds_write_b16 v0, v9 offset:9248
	v_cvt_pk_bf16_f32 v10, v2, s0
	ds_write_b16 v8, v10 offset:9248
	v_mul_f32_e32 v2, v2, v73
	v_fma_f32 v3, v3, v73, v105
	v_cvt_pk_bf16_f32 v11, v3, s0
	ds_write_b16 v0, v11 offset:9520
	v_cvt_pk_bf16_f32 v12, v2, s0
	ds_write_b16 v8, v12 offset:9520
	v_mul_f32_e32 v2, v2, v74
	v_fma_f32 v3, v3, v74, v106
	v_cvt_pk_bf16_f32 v9, v3, s0
	ds_write_b16 v0, v9 offset:9792
	v_cvt_pk_bf16_f32 v10, v2, s0
	ds_write_b16 v8, v10 offset:9792
	v_mul_f32_e32 v2, v2, v75
	v_fma_f32 v3, v3, v75, v107
	v_cvt_pk_bf16_f32 v11, v3, s0
	ds_write_b16 v0, v11 offset:10064
	v_cvt_pk_bf16_f32 v12, v2, s0
	ds_write_b16 v8, v12 offset:10064
	v_mul_f32_e32 v2, v2, v76
	v_fma_f32 v3, v3, v76, v108
	v_cvt_pk_bf16_f32 v9, v3, s0
	ds_write_b16 v0, v9 offset:10336
	v_cvt_pk_bf16_f32 v10, v2, s0
	ds_write_b16 v8, v10 offset:10336
	v_mul_f32_e32 v2, v2, v77
	v_fma_f32 v3, v3, v77, v109
	v_cvt_pk_bf16_f32 v11, v3, s0
	ds_write_b16 v0, v11 offset:10608
	v_cvt_pk_bf16_f32 v12, v2, s0
	ds_write_b16 v8, v12 offset:10608
	v_mul_f32_e32 v2, v2, v78
	v_fma_f32 v3, v3, v78, v110
	v_cvt_pk_bf16_f32 v9, v3, s0
	ds_write_b16 v0, v9 offset:10880
	v_cvt_pk_bf16_f32 v10, v2, s0
	ds_write_b16 v8, v10 offset:10880
	v_mul_f32_e32 v2, v2, v79
	v_fma_f32 v3, v3, v79, v111
	v_cvt_pk_bf16_f32 v11, v3, s0
	ds_write_b16 v0, v11 offset:11152
	v_cvt_pk_bf16_f32 v12, v2, s0
	ds_write_b16 v8, v12 offset:11152
	v_mul_f32_e32 v2, v2, v80
	v_fma_f32 v3, v3, v80, v112
	v_cvt_pk_bf16_f32 v9, v3, s0
	ds_write_b16 v0, v9 offset:11424
	v_cvt_pk_bf16_f32 v10, v2, s0
	ds_write_b16 v8, v10 offset:11424
	v_mul_f32_e32 v2, v2, v81
	v_fma_f32 v3, v3, v81, v113
	v_cvt_pk_bf16_f32 v11, v3, s0
	ds_write_b16 v0, v11 offset:11696
	v_cvt_pk_bf16_f32 v12, v2, s0
	ds_write_b16 v8, v12 offset:11696
	v_mul_f32_e32 v2, v2, v82
	v_fma_f32 v3, v3, v82, v114
	v_cvt_pk_bf16_f32 v9, v3, s0
	ds_write_b16 v0, v9 offset:11968
	v_cvt_pk_bf16_f32 v10, v2, s0
	ds_write_b16 v8, v10 offset:11968
	v_mul_f32_e32 v2, v2, v83
	v_fma_f32 v3, v3, v83, v115
	v_cvt_pk_bf16_f32 v11, v3, s0
	ds_write_b16 v0, v11 offset:12240
	v_cvt_pk_bf16_f32 v12, v2, s0
	ds_write_b16 v8, v12 offset:12240
	v_mul_f32_e32 v2, v2, v84
	v_fma_f32 v3, v3, v84, v116
	v_cvt_pk_bf16_f32 v9, v3, s0
	ds_write_b16 v0, v9 offset:12512
	v_cvt_pk_bf16_f32 v10, v2, s0
	ds_write_b16 v8, v10 offset:12512
	v_mul_f32_e32 v2, v2, v85
	v_fma_f32 v3, v3, v85, v117
	v_cvt_pk_bf16_f32 v11, v3, s0
	ds_write_b16 v0, v11 offset:12784
	v_cvt_pk_bf16_f32 v12, v2, s0
	ds_write_b16 v8, v12 offset:12784
	v_mul_f32_e32 v2, v2, v86
	v_fma_f32 v3, v3, v86, v118
	v_cvt_pk_bf16_f32 v9, v3, s0
	ds_write_b16 v0, v9 offset:13056
	v_cvt_pk_bf16_f32 v10, v2, s0
	ds_write_b16 v8, v10 offset:13056
	v_mul_f32_e32 v2, v2, v87
	v_fma_f32 v3, v3, v87, v119
	v_cvt_pk_bf16_f32 v11, v3, s0
	ds_write_b16 v0, v11 offset:13328
	v_cvt_pk_bf16_f32 v12, v2, s0
	ds_write_b16 v8, v12 offset:13328
	v_mul_f32_e32 v2, v2, v88
	v_fma_f32 v3, v3, v88, v120
	v_cvt_pk_bf16_f32 v9, v3, s0
	ds_write_b16 v0, v9 offset:13600
	v_cvt_pk_bf16_f32 v10, v2, s0
	ds_write_b16 v8, v10 offset:13600
	v_mul_f32_e32 v2, v2, v89
	v_fma_f32 v3, v3, v89, v121
	v_cvt_pk_bf16_f32 v11, v3, s0
	ds_write_b16 v0, v11 offset:13872
	v_cvt_pk_bf16_f32 v12, v2, s0
	ds_write_b16 v8, v12 offset:13872
	v_mul_f32_e32 v2, v2, v90
	v_fma_f32 v3, v3, v90, v122
	v_cvt_pk_bf16_f32 v9, v3, s0
	ds_write_b16 v0, v9 offset:14144
	v_cvt_pk_bf16_f32 v10, v2, s0
	ds_write_b16 v8, v10 offset:14144
	v_mul_f32_e32 v2, v2, v91
	v_fma_f32 v3, v3, v91, v123
	v_cvt_pk_bf16_f32 v11, v3, s0
	ds_write_b16 v0, v11 offset:14416
	v_cvt_pk_bf16_f32 v12, v2, s0
	ds_write_b16 v8, v12 offset:14416
	v_mul_f32_e32 v2, v2, v92
	v_fma_f32 v3, v3, v92, v124
	v_cvt_pk_bf16_f32 v9, v3, s0
	ds_write_b16 v0, v9 offset:14688
	v_cvt_pk_bf16_f32 v10, v2, s0
	ds_write_b16 v8, v10 offset:14688
	v_mul_f32_e32 v2, v2, v93
	v_fma_f32 v3, v3, v93, v125
	v_cvt_pk_bf16_f32 v11, v3, s0
	ds_write_b16 v0, v11 offset:14960
	v_cvt_pk_bf16_f32 v12, v2, s0
	ds_write_b16 v8, v12 offset:14960
	v_mul_f32_e32 v2, v2, v94
	v_fma_f32 v3, v3, v94, v126
	v_cvt_pk_bf16_f32 v9, v3, s0
	ds_write_b16 v0, v9 offset:15232
	v_cvt_pk_bf16_f32 v10, v2, s0
	ds_write_b16 v8, v10 offset:15232
	v_mul_f32_e32 v2, v2, v95
	v_fma_f32 v3, v3, v95, v127
	v_cvt_pk_bf16_f32 v11, v3, s0
	ds_write_b16 v0, v11 offset:15504
	v_cvt_pk_bf16_f32 v12, v2, s0
	ds_write_b16 v8, v12 offset:15504
	v_mul_f32_e32 v2, v2, v96
	v_fma_f32 v3, v3, v96, v128
	v_cvt_pk_bf16_f32 v9, v3, s0
	ds_write_b16 v0, v9 offset:15776
	v_cvt_pk_bf16_f32 v10, v2, s0
	ds_write_b16 v8, v10 offset:15776
	v_mul_f32_e32 v2, v2, v97
	v_fma_f32 v3, v3, v97, v129
	v_cvt_pk_bf16_f32 v11, v3, s0
	ds_write_b16 v0, v11 offset:16048
	v_cvt_pk_bf16_f32 v12, v2, s0
	ds_write_b16 v8, v12 offset:16048
	v_mul_f32_e32 v2, v2, v98
	v_fma_f32 v3, v3, v98, v130
	v_cvt_pk_bf16_f32 v9, v3, s0
	ds_write_b16 v0, v9 offset:16320
	v_cvt_pk_bf16_f32 v10, v2, s0
	ds_write_b16 v8, v10 offset:16320
	v_mul_f32_e32 v2, v2, v99
	v_fma_f32 v3, v3, v99, v131
	v_cvt_pk_bf16_f32 v11, v3, s0
	ds_write_b16 v0, v11 offset:16592
	v_cvt_pk_bf16_f32 v12, v2, s0
	ds_write_b16 v8, v12 offset:16592
	v_mul_f32_e32 v2, v2, v100
	v_fma_f32 v3, v3, v100, v132
	v_cvt_pk_bf16_f32 v9, v3, s0
	ds_write_b16 v0, v9 offset:16864
	v_cvt_pk_bf16_f32 v10, v2, s0
	ds_write_b16 v8, v10 offset:16864
	v_mul_f32_e32 v2, v2, v101
	v_fma_f32 v3, v3, v101, v133
	v_cvt_pk_bf16_f32 v11, v3, s0
	ds_write_b16 v0, v11 offset:17136
	v_cvt_pk_bf16_f32 v12, v2, s0
	ds_write_b16 v8, v12 offset:17136
	s_mul_i32 s4, s26, 0x300
	s_add_i32 s4, s4, s68
	v_add_u32_e32 v4, s4, v39
	v_ashrrev_i32_e32 v5, 31, v4
	v_readlane_b32 s4, v249, 34
	v_lshlrev_b64 v[4:5], 2, v[4:5]
	v_readlane_b32 s5, v249, 35
	s_nop 1
	v_lshl_add_u64 v[6:7], s[4:5], 0, v[4:5]
	v_readlane_b32 s4, v249, 36
	v_readlane_b32 s5, v249, 37
	global_store_dword v[6:7], v2, off
	s_nop 0
	v_lshl_add_u64 v[4:5], s[4:5], 0, v[4:5]
	global_store_dword v[4:5], v3, off
